# s2 + first-iteration vmcnt(8) waits of each unit skipped in G1a/G1b K-loops (epilogue ends with vmcnt(16), prologue drains to vmcnt(0))
# baseline (speedup 1.0000x reference)
; #define PG8_STAGE(bufoff, gbase, voff) do { _Pragma("unroll") for (int _i = 0; _i < 2; ++_i) \
;         __builtin_amdgcn_global_load_lds((const unsigned*)((const char*)(gbase) + (voff)[_i]), (PG8_LAS unsigned*)(lds + (bufoff) + ldsw + _i * 8192), 16, 0, 0); } while (0)
; #define PG8_WAIT_V(n) asm volatile("s_waitcnt vmcnt(" #n ")" ::: "memory")
; #define PG8_BAR __builtin_amdgcn_s_barrier()
; template <class Epi, class Sched, bool ALIGN_EPI = false, bool SP2 = false, bool I8 = false>
; __device__ __forceinline__ void gemm_phase(PG8_LAS unsigned char* lds, const Gemm g, const Sched& S, const Epi& E, const int tid) {
;     const int wid = __builtin_amdgcn_readfirstlane(tid >> 6), lane = tid & 63, wr = wid >> 2, wc = wid & 3, fr = lane & 15, fq = lane >> 4;
;     const int K = g.K, nt = K / BK;
;     unsigned voffA[2], voffB[2];
; #pragma unroll
;     for (int i = 0; i < 2; ++i) { int R, C; stage_rc(tid * 16 + i * 8192, R, C); const int Rb = Epi::PERM ? ((R & ~31) + perm32(R & 31)) : R;
;         voffA[i] = (unsigned)(R * g.lda + C) * 2u; voffB[i] = (unsigned)(Rb * g.ldb + C) * 2u; }
;     const size_t kstep = (size_t)(BK * 2);
;     const size_t hstepA = (size_t)HALF * g.lda * 2, hstepB = (size_t)HALF * g.ldb * 2;
;     const size_t tstepA = 2 * hstepA, tstepB = 2 * hstepB;
;     const unsigned ldsw = (unsigned)wid * 1024u;
;     const int aoff = lds_byte(wr * 64 + fr, fq * 8), boff = lds_byte(wc * 32 + fr, fq * 8);
;     ...
;     if constexpr (SP2) {
;         PG8_STAGE(PG8_SB(0, 0), cB, voffB); PG8_STAGE(PG8_SB(0, 1), cB + hstepB, voffB); PG8_STAGE(PG8_SA(0, 0), cA, voffA); PG8_STAGE(PG8_SA(0, 1), cA + hstepA, voffA);
;         if (wr == 1) PG8_BAR;
;         PG8_WAIT_V(2); PG8_BAR;
;         PG8_STAGE(PG8_SB(1, 0), cB + kstep, voffB); PG8_STAGE(PG8_SA(1, 0), cA + kstep, voffA); PG8_STAGE(PG8_SB(1, 1), cB + hstepB + kstep, voffB);
;         PG8_WAIT_V(6); PG8_BAR;
.LBB0_240:
	v_lshrrev_b32_e32 v16, 1, v8
	v_and_b32_e32 v16, 24, v16
	s_add_u32 s14, s14, 0x26402800
	v_and_b32_e32 v15, 15, v8
	v_lshlrev_b32_e32 v17, 1, v16
	v_lshlrev_b32_e32 v8, 2, v8
	s_addc_u32 s15, s15, 0
	v_lshl_or_b32 v140, s22, 6, v15
	v_lshl_or_b32 v15, v15, 6, v17
	s_lshl_b32 s11, s22, 13
	v_and_b32_e32 v8, 32, v8
	v_bitop3_b32 v17, v15, s11, v8 bitop3:0xde
	s_lshl_b32 s11, s23, 5
	s_and_b32 s11, s11, 0x60
	s_add_i32 m0, s13, 0x18000
	v_lshl_add_u64 v[6:7], v[6:7], 0, s[42:43]
	s_lshl_b32 s22, s11, 7
	s_waitcnt vmcnt(2)
	s_barrier
	global_load_lds_dwordx4 v[6:7], off
	v_lshl_add_u64 v[4:5], v[4:5], 0, s[42:43]
	s_add_i32 m0, s13, 0x1a000
	s_add_i32 s65, s13, 0x8000
	s_add_i32 s66, s13, 0xa000
	v_bitop3_b32 v141, s22, v15, v8 bitop3:0xf6
	global_load_lds_dwordx4 v[4:5], off
	v_lshl_add_u64 v[0:1], v[0:1], 0, s[42:43]
	s_mov_b32 m0, s65
	s_add_u32 s22, s38, 0x100080
	global_load_lds_dwordx4 v[0:1], off
	v_lshl_add_u64 v[0:1], v[2:3], 0, s[42:43]
	s_mov_b32 m0, s66
	s_addc_u32 s23, s39, 0
	global_load_lds_dwordx4 v[0:1], off
	s_add_i32 m0, s13, 0x1c000
	v_lshl_add_u64 v[0:1], s[22:23], 0, v[96:97]
	global_load_lds_dwordx4 v[0:1], off
	v_lshl_add_u64 v[0:1], s[22:23], 0, v[134:135]
	s_add_i32 m0, s13, 0x1e000
	s_cmpk_lt_u32 s24, 0x100
	global_load_lds_dwordx4 v[0:1], off
	v_lshlrev_b32_e32 v0, 16, v12
	v_and_b32_e32 v0, 0xfffe0000, v0
	v_lshl_add_u32 v0, v13, 13, v0
	v_and_b32_e32 v1, 1, v12
	v_lshl_or_b32 v0, v1, 6, v0
	v_lshl_add_u32 v136, v14, 1, v0
	v_lshlrev_b32_e32 v0, 16, v9
	s_cselect_b64 s[22:23], -1, 0
	s_cmp_lt_i32 s4, s1
	v_and_b32_e32 v0, 0xfffe0000, v0
	s_waitcnt vmcnt(0)
	s_cselect_b64 s[24:25], -1, 0
	s_or_b32 s73, s2, s26
	v_lshl_add_u32 v0, v10, 13, v0
	v_and_b32_e32 v1, 1, v9
	s_add_i32 s74, s73, s26
	s_mul_i32 s75, s3, s2
	s_mul_i32 s26, s48, s26
	v_lshl_or_b32 v0, v1, 6, v0
	s_ashr_i32 s70, s4, 31
	s_or_b32 s76, s26, s75
	v_or_b32_e32 v142, s11, v16
	v_mov_b32_e32 v137, v97
	v_lshl_add_u32 v138, v11, 1, v0
	v_mov_b32_e32 v139, v97
	s_mov_b32 s77, 0
	v_add_u32_e32 v143, 0, v17
	s_barrier
	s_branch .LBB0_243

; #define PG8_STAGE(bufoff, gbase, voff) do { _Pragma("unroll") for (int _i = 0; _i < 2; ++_i) \
;         __builtin_amdgcn_global_load_lds((const unsigned*)((const char*)(gbase) + (voff)[_i]), (PG8_LAS unsigned*)(lds + (bufoff) + ldsw + _i * 8192), 16, 0, 0); } while (0)
; #define PG8_LDA(dst, b, h) do { _Pragma("unroll") for (int m = 0; m < 4; ++m) _Pragma("unroll") for (int k = 0; k < 2; ++k) dst[m][k] = *(const PG8_LAS bf16x8*)(lds + PG8_SA(b, h) + aoff + m * 2048 + k * 1024); } while (0)
; #define PG8_LDB(dst, b, h) do { _Pragma("unroll") for (int n = 0; n < 2; ++n) _Pragma("unroll") for (int k = 0; k < 2; ++k) dst[n][k] = *(const PG8_LAS bf16x8*)(lds + PG8_SB(b, h) + boff + n * 2048 + k * 1024); } while (0)
; #define PG8_MMA(ai, bj, At, Bt) do { __builtin_amdgcn_s_setprio(1); _Pragma("unroll") for (int m = 0; m < 4; ++m) _Pragma("unroll") for (int n = 0; n < 2; ++n) _Pragma("unroll") for (int k = 0; k < 2; ++k) \
;         mma1<I8>(acc[ai][bj][m][n], Bt[n][k], At[m][k]); __builtin_amdgcn_s_setprio(0); } while (0)
; #define PG8_WAIT_V(n) asm volatile("s_waitcnt vmcnt(" #n ")" ::: "memory")
; #define PG8_WAIT_L(n) asm volatile("s_waitcnt lgkmcnt(" #n ")" ::: "memory")
; #define PG8_BAR __builtin_amdgcn_s_barrier()
; #define PG8_SCHED __builtin_amdgcn_sched_barrier(0)
; template <class Epi, class Sched, bool ALIGN_EPI = false, bool SP2 = false, bool I8 = false>
; __device__ __forceinline__ void gemm_phase(PG8_LAS unsigned char* lds, const Gemm g, const Sched& S, const Epi& E, const int tid) {
;     ...
;         for (int t = 0; t < nt; t += 2) {
;             const bool last = (t == nt - 2);
;             const char* a1 = cA + (size_t)(t + 1) * kstep;
;             const char* a2 = last ? nA : cA + (size_t)(t + 2) * kstep; const char* b2 = last ? nB : cB + (size_t)(t + 2) * kstep;
;             const char* a3 = a2 + kstep; const char* b3 = b2 + kstep;
;             if (last && has_next) S.a_ready(nxt);
;             if constexpr (SP2) {
;             PG8_LDB(B0, 0, 0); PG8_LDB(B1, 0, 1); PG8_SCHED; PG8_LDA(At, 0, 0); PG8_STAGE(PG8_SA(1, 1), a1 + hstepA, voffA);
;             PG8_WAIT_V(8); PG8_WAIT_L(0); PG8_BAR; PG8_MMA(0, 0, At, B0); PG8_MMA(0, 1, At, B1); PG8_BAR; PG8_SCHED;
;             PG8_LDA(At, 0, 1); PG8_STAGE(PG8_SB(0, 0), b2, voffB); PG8_STAGE(PG8_SB(0, 1), b2 + hstepB, voffB); PG8_STAGE(PG8_SA(0, 0), a2, voffA);
.LBB0_270:
	s_add_u32 s40, s38, 0xfff00080
	s_addc_u32 s41, s39, -1
	s_add_i32 s88, 0, 0x10000
	s_cmp_eq_u32 s87, 60
	s_cselect_b32 s47, s11, s41
	s_cselect_b32 s46, s29, s40
	s_cselect_b32 s41, s27, s86
	s_cselect_b32 s40, s80, s85
	s_add_i32 s90, 0, 0x14000
	v_add_u32_e32 v156, s88, v141
	v_add_u32_e32 v172, s90, v141
	ds_read_b128 v[144:147], v156
	ds_read_b128 v[148:151], v156 offset:1024
	ds_read_b128 v[152:155], v156 offset:2048
	ds_read_b128 v[156:159], v156 offset:3072
	ds_read_b128 v[160:163], v172
	ds_read_b128 v[164:167], v172 offset:1024
	ds_read_b128 v[168:171], v172 offset:2048
	ds_read_b128 v[172:175], v172 offset:3072
	v_lshl_add_u64 v[212:213], s[38:39], 0, v[138:139]
	s_add_i32 m0, s13, 0xc000
	ds_read_b128 v[176:179], v143
	ds_read_b128 v[180:183], v143 offset:1024
	ds_read_b128 v[184:187], v143 offset:2048
	ds_read_b128 v[188:191], v143 offset:3072
	ds_read_b128 v[192:195], v143 offset:4096
	ds_read_b128 v[200:203], v143 offset:5120
	ds_read_b128 v[204:207], v143 offset:6144
	ds_read_b128 v[208:211], v143 offset:7168
	global_load_lds_dwordx4 v[212:213], off
	v_lshl_add_u64 v[212:213], s[38:39], 0, v[136:137]
	s_add_i32 m0, s13, 0xe000
	s_nop 0
	global_load_lds_dwordx4 v[212:213], off
	s_cmp_eq_u32 s87, -2
	s_cbranch_scc1 .Ltb_g1a_1
	s_waitcnt vmcnt(8)
.Ltb_g1a_1:
	s_waitcnt lgkmcnt(0)
	s_barrier
	s_setprio 1
	s_waitcnt lgkmcnt(0)
	v_mfma_f32_16x16x32_bf16 v[126:129], v[144:147], v[176:179], v[126:129]
	v_mfma_f32_16x16x32_bf16 v[122:125], v[152:155], v[176:179], v[122:125]
	v_mfma_f32_16x16x32_bf16 v[118:121], v[144:147], v[184:187], v[118:121]
	v_mfma_f32_16x16x32_bf16 v[114:117], v[152:155], v[184:187], v[114:117]
	v_mfma_f32_16x16x32_bf16 v[102:105], v[144:147], v[192:195], v[102:105]
	v_mfma_f32_16x16x32_bf16 v[98:101], v[152:155], v[192:195], v[98:101]
	v_mfma_f32_16x16x32_bf16 v[84:87], v[144:147], v[204:207], v[84:87]
	v_mfma_f32_16x16x32_bf16 v[80:83], v[152:155], v[204:207], v[80:83]
	v_mfma_f32_16x16x32_bf16 v[126:129], v[148:151], v[180:183], v[126:129]
	v_mfma_f32_16x16x32_bf16 v[122:125], v[156:159], v[180:183], v[122:125]
	v_mfma_f32_16x16x32_bf16 v[118:121], v[148:151], v[188:191], v[118:121]
	v_mfma_f32_16x16x32_bf16 v[114:117], v[156:159], v[188:191], v[114:117]
	v_mfma_f32_16x16x32_bf16 v[102:105], v[148:151], v[200:203], v[102:105]
	v_mfma_f32_16x16x32_bf16 v[98:101], v[156:159], v[200:203], v[98:101]
	v_mfma_f32_16x16x32_bf16 v[84:87], v[148:151], v[208:211], v[84:87]
	v_mfma_f32_16x16x32_bf16 v[80:83], v[156:159], v[208:211], v[80:83]
	s_setprio 0
	s_setprio 1
	v_mfma_f32_16x16x32_bf16 v[110:113], v[160:163], v[176:179], v[110:113]
	v_mfma_f32_16x16x32_bf16 v[106:109], v[168:171], v[176:179], v[106:109]
	v_mfma_f32_16x16x32_bf16 v[92:95], v[160:163], v[184:187], v[92:95]
	v_mfma_f32_16x16x32_bf16 v[88:91], v[168:171], v[184:187], v[88:91]
	v_mfma_f32_16x16x32_bf16 v[76:79], v[160:163], v[192:195], v[76:79]
	v_mfma_f32_16x16x32_bf16 v[72:75], v[168:171], v[192:195], v[72:75]
	v_mfma_f32_16x16x32_bf16 v[68:71], v[160:163], v[204:207], v[68:71]
	v_mfma_f32_16x16x32_bf16 v[64:67], v[168:171], v[204:207], v[64:67]
	v_mfma_f32_16x16x32_bf16 v[110:113], v[164:167], v[180:183], v[110:113]
	v_mfma_f32_16x16x32_bf16 v[106:109], v[172:175], v[180:183], v[106:109]
	v_mfma_f32_16x16x32_bf16 v[92:95], v[164:167], v[188:191], v[92:95]
	v_mfma_f32_16x16x32_bf16 v[88:91], v[172:175], v[188:191], v[88:91]
	v_mfma_f32_16x16x32_bf16 v[76:79], v[164:167], v[200:203], v[76:79]
	v_mfma_f32_16x16x32_bf16 v[72:75], v[172:175], v[200:203], v[72:75]
	v_mfma_f32_16x16x32_bf16 v[68:71], v[164:167], v[208:211], v[68:71]
	v_mfma_f32_16x16x32_bf16 v[64:67], v[172:175], v[208:211], v[64:67]
	s_setprio 0
	s_barrier
	s_add_i32 s88, s88, s59
	v_lshl_add_u64 v[212:213], s[40:41], 0, v[96:97]
	s_mov_b32 m0, s88
	ds_read_b128 v[176:179], v143 offset:16384
	ds_read_b128 v[180:183], v143 offset:17408
	ds_read_b128 v[184:187], v143 offset:18432
	ds_read_b128 v[188:191], v143 offset:19456
	ds_read_b128 v[192:195], v143 offset:20480
	ds_read_b128 v[200:203], v143 offset:21504
	ds_read_b128 v[204:207], v143 offset:22528
	ds_read_b128 v[208:211], v143 offset:23552
	global_load_lds_dwordx4 v[212:213], off
	s_add_i32 m0, s88, 0x2000
	s_add_u32 s88, s40, 0x100000
	v_lshl_add_u64 v[214:215], s[40:41], 0, v[134:135]
	s_addc_u32 s89, s41, 0
	s_add_i32 s90, s90, s59
	global_load_lds_dwordx4 v[214:215], off
	v_lshl_add_u64 v[216:217], s[88:89], 0, v[96:97]
	s_mov_b32 m0, s90
	v_lshl_add_u64 v[218:219], s[46:47], 0, v[132:133]
	global_load_lds_dwordx4 v[216:217], off
	v_lshl_add_u64 v[216:217], s[88:89], 0, v[134:135]
	s_add_i32 m0, s90, 0x2000
	s_nop 0
	global_load_lds_dwordx4 v[216:217], off
	v_lshl_add_u64 v[216:217], s[46:47], 0, v[130:131]
	s_mov_b32 m0, s13
	s_nop 0
	global_load_lds_dwordx4 v[216:217], off
	s_mov_b32 m0, s60
	s_nop 0
	global_load_lds_dwordx4 v[218:219], off
	s_cmp_eq_u32 s87, -2
	s_cbranch_scc1 .Ltb_g1a_2
	s_waitcnt vmcnt(8)
; #define PG8_STAGE(bufoff, gbase, voff) do { _Pragma("unroll") for (int _i = 0; _i < 2; ++_i) \
;         __builtin_amdgcn_global_load_lds((const unsigned*)((const char*)(gbase) + (voff)[_i]), (PG8_LAS unsigned*)(lds + (bufoff) + ldsw + _i * 8192), 16, 0, 0); } while (0)
; #define PG8_LDA(dst, b, h) do { _Pragma("unroll") for (int m = 0; m < 4; ++m) _Pragma("unroll") for (int k = 0; k < 2; ++k) dst[m][k] = *(const PG8_LAS bf16x8*)(lds + PG8_SA(b, h) + aoff + m * 2048 + k * 1024); } while (0)
; #define PG8_LDB(dst, b, h) do { _Pragma("unroll") for (int n = 0; n < 2; ++n) _Pragma("unroll") for (int k = 0; k < 2; ++k) dst[n][k] = *(const PG8_LAS bf16x8*)(lds + PG8_SB(b, h) + boff + n * 2048 + k * 1024); } while (0)
; #define PG8_MMA(ai, bj, At, Bt) do { __builtin_amdgcn_s_setprio(1); _Pragma("unroll") for (int m = 0; m < 4; ++m) _Pragma("unroll") for (int n = 0; n < 2; ++n) _Pragma("unroll") for (int k = 0; k < 2; ++k) \
;         mma1<I8>(acc[ai][bj][m][n], Bt[n][k], At[m][k]); __builtin_amdgcn_s_setprio(0); } while (0)
; #define PG8_WAIT_V(n) asm volatile("s_waitcnt vmcnt(" #n ")" ::: "memory")
; #define PG8_WAIT_L(n) asm volatile("s_waitcnt lgkmcnt(" #n ")" ::: "memory")
; #define PG8_BAR __builtin_amdgcn_s_barrier()
; #define PG8_SCHED __builtin_amdgcn_sched_barrier(0)
; template <class Epi, class Sched, bool ALIGN_EPI = false, bool SP2 = false, bool I8 = false>
; __device__ __forceinline__ void gemm_phase(PG8_LAS unsigned char* lds, const Gemm g, const Sched& S, const Epi& E, const int tid) {
;     ...
;             PG8_WAIT_V(8); PG8_WAIT_L(0); PG8_BAR; PG8_MMA(1, 0, At, B0); PG8_MMA(1, 1, At, B1); PG8_BAR; PG8_SCHED;
;             PG8_LDB(B0, 1, 0); PG8_LDB(B1, 1, 1); PG8_SCHED; PG8_LDA(At, 1, 0); PG8_STAGE(PG8_SA(0, 1), a2 + hstepA, voffA);
;             PG8_WAIT_V(8); PG8_WAIT_L(0); PG8_BAR; PG8_MMA(0, 0, At, B0); PG8_MMA(0, 1, At, B1); PG8_BAR; PG8_SCHED;
.Ltb_g1a_2:
	s_waitcnt lgkmcnt(0)
	s_barrier
	s_setprio 1
	s_waitcnt lgkmcnt(0)
	v_mfma_f32_16x16x32_bf16 v[60:63], v[144:147], v[176:179], v[60:63]
	v_mfma_f32_16x16x32_bf16 v[56:59], v[152:155], v[176:179], v[56:59]
	v_mfma_f32_16x16x32_bf16 v[52:55], v[144:147], v[184:187], v[52:55]
	v_mfma_f32_16x16x32_bf16 v[48:51], v[152:155], v[184:187], v[48:51]
	v_mfma_f32_16x16x32_bf16 v[36:39], v[144:147], v[192:195], v[36:39]
	v_mfma_f32_16x16x32_bf16 v[32:35], v[152:155], v[192:195], v[32:35]
	v_mfma_f32_16x16x32_bf16 v[20:23], v[144:147], v[204:207], v[20:23]
	v_mfma_f32_16x16x32_bf16 v[16:19], v[152:155], v[204:207], v[16:19]
	v_mfma_f32_16x16x32_bf16 v[60:63], v[148:151], v[180:183], v[60:63]
	v_mfma_f32_16x16x32_bf16 v[56:59], v[156:159], v[180:183], v[56:59]
	v_mfma_f32_16x16x32_bf16 v[52:55], v[148:151], v[188:191], v[52:55]
	v_mfma_f32_16x16x32_bf16 v[48:51], v[156:159], v[188:191], v[48:51]
	v_mfma_f32_16x16x32_bf16 v[36:39], v[148:151], v[200:203], v[36:39]
	v_mfma_f32_16x16x32_bf16 v[32:35], v[156:159], v[200:203], v[32:35]
	v_mfma_f32_16x16x32_bf16 v[20:23], v[148:151], v[208:211], v[20:23]
	v_mfma_f32_16x16x32_bf16 v[16:19], v[156:159], v[208:211], v[16:19]
	s_setprio 0
	s_setprio 1
	v_mfma_f32_16x16x32_bf16 v[44:47], v[160:163], v[176:179], v[44:47]
	v_mfma_f32_16x16x32_bf16 v[40:43], v[168:171], v[176:179], v[40:43]
	v_mfma_f32_16x16x32_bf16 v[28:31], v[160:163], v[184:187], v[28:31]
	v_mfma_f32_16x16x32_bf16 v[24:27], v[168:171], v[184:187], v[24:27]
	v_mfma_f32_16x16x32_bf16 v[12:15], v[160:163], v[192:195], v[12:15]
	v_mfma_f32_16x16x32_bf16 v[8:11], v[168:171], v[192:195], v[8:11]
	v_mfma_f32_16x16x32_bf16 v[4:7], v[160:163], v[204:207], v[4:7]
	v_mfma_f32_16x16x32_bf16 v[0:3], v[168:171], v[204:207], v[0:3]
	v_mfma_f32_16x16x32_bf16 v[44:47], v[164:167], v[180:183], v[44:47]
	v_mfma_f32_16x16x32_bf16 v[40:43], v[172:175], v[180:183], v[40:43]
	v_mfma_f32_16x16x32_bf16 v[28:31], v[164:167], v[188:191], v[28:31]
	v_mfma_f32_16x16x32_bf16 v[24:27], v[172:175], v[188:191], v[24:27]
	v_mfma_f32_16x16x32_bf16 v[12:15], v[164:167], v[200:203], v[12:15]
	v_mfma_f32_16x16x32_bf16 v[8:11], v[172:175], v[200:203], v[8:11]
	v_mfma_f32_16x16x32_bf16 v[4:7], v[164:167], v[208:211], v[4:7]
	v_mfma_f32_16x16x32_bf16 v[0:3], v[172:175], v[208:211], v[0:3]
	s_setprio 0
	s_barrier
	s_add_i32 s88, 0, 0x18000
	s_add_i32 s89, 0, 0x1c000
	v_add_u32_e32 v156, s88, v141
	v_add_u32_e32 v172, s89, v141
	ds_read_b128 v[144:147], v156
	ds_read_b128 v[148:151], v156 offset:1024
	ds_read_b128 v[152:155], v156 offset:2048
	ds_read_b128 v[156:159], v156 offset:3072
	ds_read_b128 v[160:163], v172
	ds_read_b128 v[164:167], v172 offset:1024
	ds_read_b128 v[168:171], v172 offset:2048
	ds_read_b128 v[172:175], v172 offset:3072
	s_add_u32 s46, s46, 0x100000
	s_addc_u32 s47, s47, 0
	s_mov_b32 m0, s62
	v_lshl_add_u64 v[220:221], s[46:47], 0, v[130:131]
	ds_read_b128 v[176:179], v143 offset:32768
	ds_read_b128 v[180:183], v143 offset:33792
	ds_read_b128 v[184:187], v143 offset:34816
	ds_read_b128 v[188:191], v143 offset:35840
	ds_read_b128 v[192:195], v143 offset:36864
	ds_read_b128 v[200:203], v143 offset:37888
	ds_read_b128 v[204:207], v143 offset:38912
	ds_read_b128 v[208:211], v143 offset:39936
	global_load_lds_dwordx4 v[220:221], off
	v_lshl_add_u64 v[220:221], s[46:47], 0, v[132:133]
	s_mov_b32 m0, s63
	s_nop 0
	global_load_lds_dwordx4 v[220:221], off
	s_waitcnt vmcnt(8)
	s_waitcnt lgkmcnt(0)
	s_barrier
	s_setprio 1
	s_waitcnt lgkmcnt(0)
	v_mfma_f32_16x16x32_bf16 v[126:129], v[144:147], v[176:179], v[126:129]
	v_mfma_f32_16x16x32_bf16 v[122:125], v[152:155], v[176:179], v[122:125]
	v_mfma_f32_16x16x32_bf16 v[118:121], v[144:147], v[184:187], v[118:121]
	v_mfma_f32_16x16x32_bf16 v[114:117], v[152:155], v[184:187], v[114:117]
	v_mfma_f32_16x16x32_bf16 v[102:105], v[144:147], v[192:195], v[102:105]
	v_mfma_f32_16x16x32_bf16 v[98:101], v[152:155], v[192:195], v[98:101]
	v_mfma_f32_16x16x32_bf16 v[84:87], v[144:147], v[204:207], v[84:87]
	v_mfma_f32_16x16x32_bf16 v[80:83], v[152:155], v[204:207], v[80:83]
	v_mfma_f32_16x16x32_bf16 v[126:129], v[148:151], v[180:183], v[126:129]
	v_mfma_f32_16x16x32_bf16 v[122:125], v[156:159], v[180:183], v[122:125]
	v_mfma_f32_16x16x32_bf16 v[118:121], v[148:151], v[188:191], v[118:121]
	v_mfma_f32_16x16x32_bf16 v[114:117], v[156:159], v[188:191], v[114:117]
	v_mfma_f32_16x16x32_bf16 v[102:105], v[148:151], v[200:203], v[102:105]
	v_mfma_f32_16x16x32_bf16 v[98:101], v[156:159], v[200:203], v[98:101]
	v_mfma_f32_16x16x32_bf16 v[84:87], v[148:151], v[208:211], v[84:87]
	v_mfma_f32_16x16x32_bf16 v[80:83], v[156:159], v[208:211], v[80:83]
	s_setprio 0
	s_setprio 1
	v_mfma_f32_16x16x32_bf16 v[110:113], v[160:163], v[176:179], v[110:113]
	v_mfma_f32_16x16x32_bf16 v[106:109], v[168:171], v[176:179], v[106:109]
	v_mfma_f32_16x16x32_bf16 v[92:95], v[160:163], v[184:187], v[92:95]
	v_mfma_f32_16x16x32_bf16 v[88:91], v[168:171], v[184:187], v[88:91]
	v_mfma_f32_16x16x32_bf16 v[76:79], v[160:163], v[192:195], v[76:79]
	v_mfma_f32_16x16x32_bf16 v[72:75], v[168:171], v[192:195], v[72:75]
	v_mfma_f32_16x16x32_bf16 v[68:71], v[160:163], v[204:207], v[68:71]
	v_mfma_f32_16x16x32_bf16 v[64:67], v[168:171], v[204:207], v[64:67]
	v_mfma_f32_16x16x32_bf16 v[110:113], v[164:167], v[180:183], v[110:113]
	v_mfma_f32_16x16x32_bf16 v[106:109], v[172:175], v[180:183], v[106:109]
	v_mfma_f32_16x16x32_bf16 v[92:95], v[164:167], v[188:191], v[92:95]
	v_mfma_f32_16x16x32_bf16 v[88:91], v[172:175], v[188:191], v[88:91]
	v_mfma_f32_16x16x32_bf16 v[76:79], v[164:167], v[200:203], v[76:79]
	v_mfma_f32_16x16x32_bf16 v[72:75], v[172:175], v[200:203], v[72:75]
	v_mfma_f32_16x16x32_bf16 v[68:71], v[164:167], v[208:211], v[68:71]
	v_mfma_f32_16x16x32_bf16 v[64:67], v[172:175], v[208:211], v[64:67]
	s_setprio 0
	s_barrier
; #define PG8_STAGE(bufoff, gbase, voff) do { _Pragma("unroll") for (int _i = 0; _i < 2; ++_i) \
;         __builtin_amdgcn_global_load_lds((const unsigned*)((const char*)(gbase) + (voff)[_i]), (PG8_LAS unsigned*)(lds + (bufoff) + ldsw + _i * 8192), 16, 0, 0); } while (0)
; #define PG8_LDA(dst, b, h) do { _Pragma("unroll") for (int m = 0; m < 4; ++m) _Pragma("unroll") for (int k = 0; k < 2; ++k) dst[m][k] = *(const PG8_LAS bf16x8*)(lds + PG8_SA(b, h) + aoff + m * 2048 + k * 1024); } while (0)
; #define PG8_WAIT_V(n) asm volatile("s_waitcnt vmcnt(" #n ")" ::: "memory")
; #define PG8_WAIT_L(n) asm volatile("s_waitcnt lgkmcnt(" #n ")" ::: "memory")
; template <class Epi, class Sched, bool ALIGN_EPI = false, bool SP2 = false, bool I8 = false>
; __device__ __forceinline__ void gemm_phase(PG8_LAS unsigned char* lds, const Gemm g, const Sched& S, const Epi& E, const int tid) {
;     ...
;         for (int t = 0; t < nt; t += 2) {
;             const bool last = (t == nt - 2);
;             const char* a1 = cA + (size_t)(t + 1) * kstep;
;             const char* a2 = last ? nA : cA + (size_t)(t + 2) * kstep; const char* b2 = last ? nB : cB + (size_t)(t + 2) * kstep;
;             const char* a3 = a2 + kstep; const char* b3 = b2 + kstep;
;             if (last && has_next) S.a_ready(nxt);
;             if constexpr (SP2) {
;             PG8_LDB(B0, 0, 0); PG8_LDB(B1, 0, 1); PG8_SCHED; PG8_LDA(At, 0, 0); PG8_STAGE(PG8_SA(1, 1), a1 + hstepA, voffA);
;             PG8_WAIT_V(8); PG8_WAIT_L(0); PG8_BAR; PG8_MMA(0, 0, At, B0); PG8_MMA(0, 1, At, B1); PG8_BAR; PG8_SCHED;
;             PG8_LDA(At, 0, 1); PG8_STAGE(PG8_SB(0, 0), b2, voffB); PG8_STAGE(PG8_SB(0, 1), b2 + hstepB, voffB); PG8_STAGE(PG8_SA(0, 0), a2, voffA);
;             PG8_WAIT_V(8); PG8_WAIT_L(0); PG8_BAR; PG8_MMA(1, 0, At, B0); PG8_MMA(1, 1, At, B1); PG8_BAR; PG8_SCHED;
;             PG8_LDB(B0, 1, 0); PG8_LDB(B1, 1, 1); PG8_SCHED; PG8_LDA(At, 1, 0); PG8_STAGE(PG8_SA(0, 1), a2 + hstepA, voffA);
;             PG8_WAIT_V(8); PG8_WAIT_L(0); PG8_BAR; PG8_MMA(0, 0, At, B0); PG8_MMA(0, 1, At, B1); PG8_BAR; PG8_SCHED;
;             PG8_LDA(At, 1, 1); PG8_STAGE(PG8_SB(1, 0), b3, voffB); PG8_STAGE(PG8_SB(1, 1), b3 + hstepB, voffB); PG8_STAGE(PG8_SA(1, 0), a3, voffA);
;             PG8_WAIT_V(8); PG8_WAIT_L(0); PG8_BAR; PG8_MMA(1, 0, At, B0); PG8_MMA(1, 1, At, B1); PG8_BAR; PG8_SCHED;
	s_add_i32 s46, s88, s59
	v_lshl_add_u64 v[212:213], v[212:213], 0, s[42:43]
	s_mov_b32 m0, s46
	ds_read_b128 v[176:179], v143 offset:49152
	ds_read_b128 v[180:183], v143 offset:50176
	ds_read_b128 v[184:187], v143 offset:51200
	ds_read_b128 v[188:191], v143 offset:52224
	ds_read_b128 v[192:195], v143 offset:53248
	ds_read_b128 v[200:203], v143 offset:54272
	ds_read_b128 v[204:207], v143 offset:55296
	ds_read_b128 v[208:211], v143 offset:56320
	global_load_lds_dwordx4 v[212:213], off
	s_add_i32 m0, s46, 0x2000
	s_add_u32 s40, s40, 0x100080
	v_lshl_add_u64 v[212:213], v[214:215], 0, s[42:43]
	s_addc_u32 s41, s41, 0
	s_add_i32 s46, s89, s59
	global_load_lds_dwordx4 v[212:213], off
	v_lshl_add_u64 v[212:213], s[40:41], 0, v[96:97]
	s_mov_b32 m0, s46
	s_nop 0
	global_load_lds_dwordx4 v[212:213], off
	v_lshl_add_u64 v[212:213], s[40:41], 0, v[134:135]
	s_add_i32 m0, s46, 0x2000
	s_nop 0
	global_load_lds_dwordx4 v[212:213], off
	v_lshl_add_u64 v[212:213], v[216:217], 0, s[42:43]
	s_mov_b32 m0, s65
	s_nop 0
	global_load_lds_dwordx4 v[212:213], off
	v_lshl_add_u64 v[212:213], v[218:219], 0, s[42:43]
	s_mov_b32 m0, s66
	s_nop 0
	global_load_lds_dwordx4 v[212:213], off
	s_waitcnt vmcnt(8)
	s_waitcnt lgkmcnt(0)
	s_barrier
	s_setprio 1
	s_waitcnt lgkmcnt(0)
	v_mfma_f32_16x16x32_bf16 v[60:63], v[144:147], v[176:179], v[60:63]
	v_mfma_f32_16x16x32_bf16 v[56:59], v[152:155], v[176:179], v[56:59]
	v_mfma_f32_16x16x32_bf16 v[52:55], v[144:147], v[184:187], v[52:55]
	v_mfma_f32_16x16x32_bf16 v[48:51], v[152:155], v[184:187], v[48:51]
	v_mfma_f32_16x16x32_bf16 v[36:39], v[144:147], v[192:195], v[36:39]
	v_mfma_f32_16x16x32_bf16 v[32:35], v[152:155], v[192:195], v[32:35]
	v_mfma_f32_16x16x32_bf16 v[20:23], v[144:147], v[204:207], v[20:23]
	v_mfma_f32_16x16x32_bf16 v[16:19], v[152:155], v[204:207], v[16:19]
	v_mfma_f32_16x16x32_bf16 v[60:63], v[148:151], v[180:183], v[60:63]
	v_mfma_f32_16x16x32_bf16 v[56:59], v[156:159], v[180:183], v[56:59]
	v_mfma_f32_16x16x32_bf16 v[52:55], v[148:151], v[188:191], v[52:55]
	v_mfma_f32_16x16x32_bf16 v[48:51], v[156:159], v[188:191], v[48:51]
	v_mfma_f32_16x16x32_bf16 v[36:39], v[148:151], v[200:203], v[36:39]
	v_mfma_f32_16x16x32_bf16 v[32:35], v[156:159], v[200:203], v[32:35]
	v_mfma_f32_16x16x32_bf16 v[20:23], v[148:151], v[208:211], v[20:23]
	v_mfma_f32_16x16x32_bf16 v[16:19], v[156:159], v[208:211], v[16:19]
	s_setprio 0
	s_setprio 1
	v_mfma_f32_16x16x32_bf16 v[44:47], v[160:163], v[176:179], v[44:47]
	v_mfma_f32_16x16x32_bf16 v[40:43], v[168:171], v[176:179], v[40:43]
	v_mfma_f32_16x16x32_bf16 v[28:31], v[160:163], v[184:187], v[28:31]
	v_mfma_f32_16x16x32_bf16 v[24:27], v[168:171], v[184:187], v[24:27]
	v_mfma_f32_16x16x32_bf16 v[12:15], v[160:163], v[192:195], v[12:15]
	v_mfma_f32_16x16x32_bf16 v[8:11], v[168:171], v[192:195], v[8:11]
	v_mfma_f32_16x16x32_bf16 v[4:7], v[160:163], v[204:207], v[4:7]
	v_mfma_f32_16x16x32_bf16 v[0:3], v[168:171], v[204:207], v[0:3]
	v_mfma_f32_16x16x32_bf16 v[44:47], v[164:167], v[180:183], v[44:47]
	v_mfma_f32_16x16x32_bf16 v[40:43], v[172:175], v[180:183], v[40:43]
	v_mfma_f32_16x16x32_bf16 v[28:31], v[164:167], v[188:191], v[28:31]
	v_mfma_f32_16x16x32_bf16 v[24:27], v[172:175], v[188:191], v[24:27]
	v_mfma_f32_16x16x32_bf16 v[12:15], v[164:167], v[200:203], v[12:15]
	v_mfma_f32_16x16x32_bf16 v[8:11], v[172:175], v[200:203], v[8:11]
	v_mfma_f32_16x16x32_bf16 v[4:7], v[164:167], v[208:211], v[4:7]
	v_mfma_f32_16x16x32_bf16 v[0:3], v[172:175], v[208:211], v[0:3]
	s_setprio 0
	s_barrier
	s_add_i32 s87, s87, 2
	s_add_u32 s85, s85, 0x100
	s_addc_u32 s86, s86, 0
	s_add_u32 s38, s38, 0x100
	s_addc_u32 s39, s39, 0
	s_cmp_gt_u32 s87, 61
	s_cbranch_scc0 .LBB0_270
	s_and_b64 vcc, exec, s[22:23]
	s_cbranch_vccz .LBB0_273
	s_barrier
; __device__ __forceinline__ unsigned cvt_pk_bf16(float lo, float hi) { const f32x2_t_ v = {lo, hi}; return __builtin_bit_cast(unsigned, __builtin_convertvector(v, bf16x2_t_)); }
; __device__ __forceinline__ float sigmoidf_(float x) { return __builtin_amdgcn_rcpf(1.0f + __expf(-x)); }
;     __device__ __forceinline__ void operator()(const f32x4 (&acc)[2][2][4][2], const Unit& u, int wr, int wc, int fr, int fq) const {
;         const int row0 = u.pm * BM + wr * 64 + fr, col0 = u.pn * BM + wc * 32 + 8 * fq;
; #pragma unroll
;         for (int ai = 0; ai < 2; ++ai)
; #pragma unroll
;             for (int m = 0; m < 4; ++m) { bf16_t* rowp = O + (size_t)(row0 + ai * HALF + m * 16) * ldc + col0;
; #pragma unroll
;                 for (int bj = 0; bj < 2; ++bj) { f32x4 v0 = acc[ai][bj][m][0], v1 = acc[ai][bj][m][1];
;                     if (u.pn >= sig_from) {
; #pragma unroll
;                         for (int e = 0; e < 4; ++e) { v0[e] = sigmoidf_(v0[e]); v1[e] = sigmoidf_(v1[e]); } }
;                     u32x4 w; w.x = cvt_pk_bf16(v0[0], v0[1]); w.y = cvt_pk_bf16(v0[2], v0[3]); w.z = cvt_pk_bf16(v1[0], v1[1]); w.w = cvt_pk_bf16(v1[2], v1[3]);
;                     *(u32x4*)(rowp + bj * HALF) = w; } }
; template <class Epi, class Sched, bool ALIGN_EPI = false, bool SP2 = false, bool I8 = false>
; __device__ __forceinline__ void gemm_phase(PG8_LAS unsigned char* lds, const Gemm g, const Sched& S, const Epi& E, const int tid) {
;     ...
;         if constexpr (!Epi::AFTER_DRAIN) { E(acc, cur, wr, wc, fr, fq); S.done(cur); }
;         if (!has_next) break;
; #pragma unroll
;         for (int a = 0; a < 2; ++a)
; #pragma unroll
;             for (int b = 0; b < 2; ++b)
; #pragma unroll
;                 for (int m = 0; m < 4; ++m)
; #pragma unroll
;                     for (int n = 0; n < 2; ++n) acc[a][b][m][n] = AccT<I8>::zero();
;         cur = nxt; cA = nA; cB = nB; ++ui;
.LBB0_273:
	v_lshl_or_b32 v144, s10, 8, v142
	v_lshl_add_u32 v150, s12, 8, v140
	v_ashrrev_i32_e32 v145, 31, v144
	v_mov_b64_e32 v[146:147], s[14:15]
	v_cvt_pk_bf16_f32 v68, v68, v69
	v_cvt_pk_bf16_f32 v69, v70, v71
	v_cvt_pk_bf16_f32 v70, v64, v65
	v_add_u32_e32 v64, 0x80, v150
	v_mad_i64_i32 v[148:149], s[10:11], v150, s64, v[146:147]
	v_lshlrev_b64 v[144:145], 1, v[144:145]
	v_cvt_pk_bf16_f32 v110, v110, v111
	v_cvt_pk_bf16_f32 v111, v112, v113
	v_cvt_pk_bf16_f32 v112, v106, v107
	v_or_b32_e32 v106, 16, v150
	v_mad_i64_i32 v[64:65], s[10:11], v64, s64, v[146:147]
	v_cvt_pk_bf16_f32 v44, v44, v45
	v_cvt_pk_bf16_f32 v45, v46, v47
	v_cvt_pk_bf16_f32 v46, v40, v41
	v_add_u32_e32 v40, 0x90, v150
	v_lshl_add_u64 v[148:149], v[148:149], 0, v[144:145]
	v_cvt_pk_bf16_f32 v113, v108, v109
	v_mad_i64_i32 v[106:107], s[10:11], v106, s64, v[146:147]
	v_cvt_pk_bf16_f32 v92, v92, v93
	v_cvt_pk_bf16_f32 v93, v94, v95
	v_cvt_pk_bf16_f32 v94, v88, v89
	v_or_b32_e32 v88, 32, v150
	v_lshl_add_u64 v[64:65], v[64:65], 0, v[144:145]
	v_cvt_pk_bf16_f32 v47, v42, v43
	v_mad_i64_i32 v[40:41], s[10:11], v40, s64, v[146:147]
	v_cvt_pk_bf16_f32 v28, v28, v29
	v_cvt_pk_bf16_f32 v29, v30, v31
	v_cvt_pk_bf16_f32 v30, v24, v25
	v_add_u32_e32 v24, 0xa0, v150
	global_store_dwordx4 v[148:149], v[110:113], off offset:256
	v_cvt_pk_bf16_f32 v95, v90, v91
	v_mad_i64_i32 v[88:89], s[10:11], v88, s64, v[146:147]
	v_lshl_add_u64 v[110:111], v[106:107], 0, v[144:145]
	v_cvt_pk_bf16_f32 v76, v76, v77
	v_cvt_pk_bf16_f32 v77, v78, v79
	v_cvt_pk_bf16_f32 v78, v72, v73
	v_or_b32_e32 v72, 48, v150
	global_store_dwordx4 v[64:65], v[44:47], off offset:256
	v_cvt_pk_bf16_f32 v31, v26, v27
	v_mad_i64_i32 v[24:25], s[10:11], v24, s64, v[146:147]
	v_lshl_add_u64 v[44:45], v[40:41], 0, v[144:145]
	v_cvt_pk_bf16_f32 v12, v12, v13
	v_cvt_pk_bf16_f32 v13, v14, v15
	v_cvt_pk_bf16_f32 v14, v8, v9
	v_add_u32_e32 v8, 0xb0, v150
	global_store_dwordx4 v[110:111], v[92:95], off offset:256
	v_cvt_pk_bf16_f32 v79, v74, v75
	v_mad_i64_i32 v[72:73], s[10:11], v72, s64, v[146:147]
	v_lshl_add_u64 v[92:93], v[88:89], 0, v[144:145]
	global_store_dwordx4 v[44:45], v[28:31], off offset:256
	v_cvt_pk_bf16_f32 v15, v10, v11
	v_mad_i64_i32 v[8:9], s[10:11], v8, s64, v[146:147]
	v_lshl_add_u64 v[28:29], v[24:25], 0, v[144:145]
	v_cvt_pk_bf16_f32 v126, v126, v127
	v_cvt_pk_bf16_f32 v127, v128, v129
	v_cvt_pk_bf16_f32 v128, v122, v123
	v_cvt_pk_bf16_f32 v129, v124, v125
	v_cvt_pk_bf16_f32 v106, v118, v119
	v_cvt_pk_bf16_f32 v107, v120, v121
	v_cvt_pk_bf16_f32 v108, v114, v115
	v_cvt_pk_bf16_f32 v109, v116, v117
	v_cvt_pk_bf16_f32 v88, v102, v103
	v_cvt_pk_bf16_f32 v89, v104, v105
	v_cvt_pk_bf16_f32 v90, v98, v99
	v_cvt_pk_bf16_f32 v91, v100, v101
	global_store_dwordx4 v[92:93], v[76:79], off offset:256
	v_cvt_pk_bf16_f32 v74, v80, v81
	v_cvt_pk_bf16_f32 v75, v82, v83
	v_lshl_add_u64 v[76:77], v[72:73], 0, v[144:145]
	v_cvt_pk_bf16_f32 v72, v84, v85
	v_cvt_pk_bf16_f32 v73, v86, v87
	v_cvt_pk_bf16_f32 v71, v66, v67
	v_cvt_pk_bf16_f32 v60, v60, v61
	v_cvt_pk_bf16_f32 v61, v62, v63
	v_cvt_pk_bf16_f32 v62, v56, v57
	v_cvt_pk_bf16_f32 v63, v58, v59
	v_cvt_pk_bf16_f32 v40, v52, v53
	v_cvt_pk_bf16_f32 v41, v54, v55
	v_cvt_pk_bf16_f32 v42, v48, v49
	v_cvt_pk_bf16_f32 v43, v50, v51
	v_cvt_pk_bf16_f32 v24, v36, v37
	v_cvt_pk_bf16_f32 v25, v38, v39
	v_cvt_pk_bf16_f32 v26, v32, v33
	v_cvt_pk_bf16_f32 v27, v34, v35
	global_store_dwordx4 v[28:29], v[12:15], off offset:256
	v_cvt_pk_bf16_f32 v10, v16, v17
	v_cvt_pk_bf16_f32 v11, v18, v19
	v_lshl_add_u64 v[12:13], v[8:9], 0, v[144:145]
	v_cvt_pk_bf16_f32 v8, v20, v21
	v_cvt_pk_bf16_f32 v9, v22, v23
	v_cvt_pk_bf16_f32 v4, v4, v5
	v_cvt_pk_bf16_f32 v5, v6, v7
	v_cvt_pk_bf16_f32 v6, v0, v1
	v_cvt_pk_bf16_f32 v7, v2, v3
	s_andn2_b64 vcc, exec, s[34:35]
	s_mov_b64 s[10:11], -1
	s_mov_b64 s[86:87], 0x5000
	s_mov_b64 s[90:91], 0x1800
	global_store_dwordx4 v[148:149], v[126:129], off
	global_store_dwordx4 v[110:111], v[106:109], off
	global_store_dwordx4 v[92:93], v[88:91], off
	global_store_dwordx4 v[76:77], v[72:75], off
	global_store_dwordx4 v[76:77], v[68:71], off offset:256
	global_store_dwordx4 v[64:65], v[60:63], off
	global_store_dwordx4 v[44:45], v[40:43], off
	global_store_dwordx4 v[28:29], v[24:27], off
	global_store_dwordx4 v[12:13], v[8:11], off
	global_store_dwordx4 v[12:13], v[4:7], off offset:256
	s_waitcnt vmcnt(16)
	s_cbranch_vccnz .LBB0_242
	s_andn2_b64 vcc, exec, s[8:9]
	s_cbranch_vccnz .LBB0_241
	s_barrier
	s_branch .LBB0_241

; #define PG8_STAGE(bufoff, gbase, voff) do { _Pragma("unroll") for (int _i = 0; _i < 2; ++_i) \
;         __builtin_amdgcn_global_load_lds((const unsigned*)((const char*)(gbase) + (voff)[_i]), (PG8_LAS unsigned*)(lds + (bufoff) + ldsw + _i * 8192), 16, 0, 0); } while (0)
; #define PG8_WAIT_V(n) asm volatile("s_waitcnt vmcnt(" #n ")" ::: "memory")
; #define PG8_BAR __builtin_amdgcn_s_barrier()
; template <class Epi, class Sched, bool ALIGN_EPI = false, bool SP2 = false, bool I8 = false>
; __device__ __forceinline__ void gemm_phase(PG8_LAS unsigned char* lds, const Gemm g, const Sched& S, const Epi& E, const int tid) {
;     const int wid = __builtin_amdgcn_readfirstlane(tid >> 6), lane = tid & 63, wr = wid >> 2, wc = wid & 3, fr = lane & 15, fq = lane >> 4;
;     const int K = g.K, nt = K / BK;
;     unsigned voffA[2], voffB[2];
; #pragma unroll
;     for (int i = 0; i < 2; ++i) { int R, C; stage_rc(tid * 16 + i * 8192, R, C); const int Rb = Epi::PERM ? ((R & ~31) + perm32(R & 31)) : R;
;         voffA[i] = (unsigned)(R * g.lda + C) * 2u; voffB[i] = (unsigned)(Rb * g.ldb + C) * 2u; }
;     const size_t kstep = (size_t)(BK * 2);
;     const size_t hstepA = (size_t)HALF * g.lda * 2, hstepB = (size_t)HALF * g.ldb * 2;
;     const size_t tstepA = 2 * hstepA, tstepB = 2 * hstepB;
;     const unsigned ldsw = (unsigned)wid * 1024u;
;     const int aoff = lds_byte(wr * 64 + fr, fq * 8), boff = lds_byte(wc * 32 + fr, fq * 8);
;     ...
;         PG8_STAGE(PG8_SB(0, 0), cB, voffB); PG8_STAGE(PG8_SB(0, 1), cB + hstepB, voffB); PG8_STAGE(PG8_SA(0, 0), cA, voffA); PG8_STAGE(PG8_SA(0, 1), cA + hstepA, voffA);
;         if (wr == 1) PG8_BAR;
;         PG8_WAIT_V(2); PG8_BAR;
;         PG8_STAGE(PG8_SB(1, 0), cB + kstep, voffB); PG8_STAGE(PG8_SA(1, 0), cA + kstep, voffA); PG8_STAGE(PG8_SB(1, 1), cB + hstepB + kstep, voffB);
;         PG8_WAIT_V(6); PG8_BAR;
.LBB0_302:
	s_add_u32 s14, s12, 0x26400000
	s_addc_u32 s15, s13, 0
	s_add_u32 s22, s12, 0x6fe00000
	s_mul_i32 s24, s97, 0x4400
	s_mov_b32 s25, s17
	s_addc_u32 s23, s13, 0
	s_lshl_b64 s[24:25], s[24:25], 2
	s_add_u32 s5, s12, s24
	v_lshrrev_b32_e32 v16, 1, v8
	s_addc_u32 s12, s13, s25
	v_and_b32_e32 v16, 24, v16
	s_add_u32 s24, s5, 0x6ff00000
	v_and_b32_e32 v15, 15, v8
	v_lshlrev_b32_e32 v17, 1, v16
	v_lshlrev_b32_e32 v8, 2, v8
	s_addc_u32 s25, s12, 0
	v_lshl_or_b32 v186, s27, 6, v15
	v_lshl_or_b32 v15, v15, 6, v17
	s_lshl_b32 s5, s27, 13
	v_and_b32_e32 v8, 32, v8
	v_bitop3_b32 v17, v15, s5, v8 bitop3:0xde
	s_lshl_b32 s5, s28, 5
	s_and_b32 s5, s5, 0x60
	s_add_i32 m0, s80, 0x18000
	v_lshl_add_u64 v[6:7], v[6:7], 0, s[42:43]
	s_lshl_b32 s12, s5, 7
	s_waitcnt vmcnt(2)
	s_barrier
	global_load_lds_dwordx4 v[6:7], off
	v_lshl_add_u64 v[4:5], v[4:5], 0, s[42:43]
	s_add_i32 m0, s80, 0x1a000
	s_add_i32 s89, s80, 0x8000
	s_add_i32 s90, s80, 0xa000
	v_bitop3_b32 v187, s12, v15, v8 bitop3:0xf6
	global_load_lds_dwordx4 v[4:5], off
	v_lshl_add_u64 v[0:1], v[0:1], 0, s[42:43]
	s_mov_b32 m0, s89
	s_add_u32 s12, s46, 0x80080
	global_load_lds_dwordx4 v[0:1], off
	v_lshl_add_u64 v[0:1], v[2:3], 0, s[42:43]
	s_mov_b32 m0, s90
	s_addc_u32 s13, s47, 0
	global_load_lds_dwordx4 v[0:1], off
	s_add_i32 m0, s80, 0x1c000
	v_lshl_add_u64 v[0:1], s[12:13], 0, v[96:97]
	global_load_lds_dwordx4 v[0:1], off
	v_lshl_add_u64 v[0:1], s[12:13], 0, v[150:151]
	s_add_i32 m0, s80, 0x1e000
	s_cmpk_lt_u32 s26, 0x100
	global_load_lds_dwordx4 v[0:1], off
	v_lshlrev_b32_e32 v0, 15, v12
	v_and_b32_e32 v0, 0xffff0000, v0
	v_lshl_add_u32 v0, v13, 12, v0
	v_and_b32_e32 v1, 1, v12
	v_lshl_or_b32 v0, v1, 6, v0
	v_lshl_add_u32 v152, v14, 1, v0
	v_lshlrev_b32_e32 v0, 15, v9
	v_and_b32_e32 v0, 0xffff0000, v0
	s_waitcnt vmcnt(0)
	s_cselect_b64 s[26:27], -1, 0
	s_cmp_lt_i32 s8, s63
	v_lshl_add_u32 v0, v10, 12, v0
	v_and_b32_e32 v1, 1, v9
	s_cselect_b64 s[28:29], -1, 0
	s_or_b32 s92, s2, s30
	v_lshl_or_b32 v0, v1, 6, v0
	s_ashr_i32 s91, s8, 31
	s_or_b32 s93, s31, s92
	s_mul_i32 s94, s48, s30
	s_sub_i32 s95, s3, s92
	v_or_b32_e32 v188, s5, v16
	v_mov_b32_e32 v153, v97
	v_lshl_add_u32 v154, v11, 1, v0
	v_mov_b32_e32 v155, v97
	s_mov_b32 s96, 0
	v_add_u32_e32 v189, 0, v17
	s_barrier
	s_branch .LBB0_305

; #define PG8_STAGE(bufoff, gbase, voff) do { _Pragma("unroll") for (int _i = 0; _i < 2; ++_i) \
;         __builtin_amdgcn_global_load_lds((const unsigned*)((const char*)(gbase) + (voff)[_i]), (PG8_LAS unsigned*)(lds + (bufoff) + ldsw + _i * 8192), 16, 0, 0); } while (0)
; #define PG8_LDA(dst, b, h) do { _Pragma("unroll") for (int m = 0; m < 4; ++m) _Pragma("unroll") for (int k = 0; k < 2; ++k) dst[m][k] = *(const PG8_LAS bf16x8*)(lds + PG8_SA(b, h) + aoff + m * 2048 + k * 1024); } while (0)
; #define PG8_LDB(dst, b, h) do { _Pragma("unroll") for (int n = 0; n < 2; ++n) _Pragma("unroll") for (int k = 0; k < 2; ++k) dst[n][k] = *(const PG8_LAS bf16x8*)(lds + PG8_SB(b, h) + boff + n * 2048 + k * 1024); } while (0)
; #define PG8_MMA(ai, bj, At, Bt) do { __builtin_amdgcn_s_setprio(1); _Pragma("unroll") for (int m = 0; m < 4; ++m) _Pragma("unroll") for (int n = 0; n < 2; ++n) _Pragma("unroll") for (int k = 0; k < 2; ++k) \
;         mma1<I8>(acc[ai][bj][m][n], Bt[n][k], At[m][k]); __builtin_amdgcn_s_setprio(0); } while (0)
; #define PG8_WAIT_V(n) asm volatile("s_waitcnt vmcnt(" #n ")" ::: "memory")
; #define PG8_WAIT_L(n) asm volatile("s_waitcnt lgkmcnt(" #n ")" ::: "memory")
; #define PG8_BAR __builtin_amdgcn_s_barrier()
; #define PG8_SCHED __builtin_amdgcn_sched_barrier(0)
; template <class Epi, class Sched, bool ALIGN_EPI = false, bool SP2 = false, bool I8 = false>
; __device__ __forceinline__ void gemm_phase(PG8_LAS unsigned char* lds, const Gemm g, const Sched& S, const Epi& E, const int tid) {
;     ...
;             PG8_LDB(B0, 0, 0); PG8_LDB(B1, 0, 1); PG8_SCHED; PG8_LDA(At, 0, 0); PG8_STAGE(PG8_SA(1, 1), a1 + hstepA, voffA);
;             PG8_WAIT_V(8); PG8_WAIT_L(0); PG8_BAR; PG8_MMA(0, 0, At, B0); PG8_MMA(0, 1, At, B1); PG8_BAR; PG8_SCHED;
;             PG8_LDA(At, 0, 1); PG8_STAGE(PG8_SB(0, 0), b2, voffB); PG8_STAGE(PG8_SB(0, 1), b2 + hstepB, voffB); PG8_STAGE(PG8_SA(0, 0), a2, voffA);
;             PG8_WAIT_V(8); PG8_WAIT_L(0); PG8_BAR; PG8_MMA(1, 0, At, B0); PG8_MMA(1, 1, At, B1); PG8_BAR; PG8_SCHED;
.LBB0_335:
	s_add_u32 s54, s46, 0xfff80080
	s_addc_u32 s55, s47, -1
	s_add_i32 s70, 0, 0x10000
	s_cmp_eq_u32 s65, 28
	s_cselect_b32 s57, s5, s55
	s_cselect_b32 s56, s31, s54
	s_cselect_b32 s55, s13, s60
	s_cselect_b32 s54, s41, s49
	s_add_i32 s87, 0, 0x14000
	v_add_u32_e32 v68, s70, v187
	v_add_u32_e32 v168, s87, v187
	ds_read_b128 v[48:51], v68
	ds_read_b128 v[52:55], v68 offset:1024
	ds_read_b128 v[64:67], v68 offset:2048
	ds_read_b128 v[68:71], v68 offset:3072
	ds_read_b128 v[156:159], v168
	ds_read_b128 v[160:163], v168 offset:1024
	ds_read_b128 v[164:167], v168 offset:2048
	ds_read_b128 v[168:171], v168 offset:3072
	v_lshl_add_u64 v[184:185], s[46:47], 0, v[154:155]
	s_add_i32 m0, s80, 0xc000
	ds_read_b128 v[172:175], v189
	ds_read_b128 v[176:179], v189 offset:1024
	ds_read_b128 v[180:183], v189 offset:2048
	ds_read_b128 v[190:193], v189 offset:3072
	ds_read_b128 v[200:203], v189 offset:4096
	ds_read_b128 v[204:207], v189 offset:5120
	ds_read_b128 v[208:211], v189 offset:6144
	ds_read_b128 v[212:215], v189 offset:7168
	global_load_lds_dwordx4 v[184:185], off
	v_lshl_add_u64 v[184:185], s[46:47], 0, v[152:153]
	s_add_i32 m0, s80, 0xe000
	s_nop 0
	global_load_lds_dwordx4 v[184:185], off
	s_cmp_eq_u32 s65, -2
	s_cbranch_scc1 .Ltb_g1b_1
	s_waitcnt vmcnt(8)
.Ltb_g1b_1:
	s_waitcnt lgkmcnt(0)
	s_barrier
	s_setprio 1
	s_waitcnt lgkmcnt(0)
	v_mfma_i32_16x16x64_i8 v[142:145], v[48:51], v[172:175], v[142:145]
	v_mfma_i32_16x16x64_i8 v[138:141], v[64:67], v[172:175], v[138:141]
	v_mfma_i32_16x16x64_i8 v[126:129], v[48:51], v[180:183], v[126:129]
	v_mfma_i32_16x16x64_i8 v[122:125], v[64:67], v[180:183], v[122:125]
	v_mfma_i32_16x16x64_i8 v[110:113], v[48:51], v[200:203], v[110:113]
	v_mfma_i32_16x16x64_i8 v[106:109], v[64:67], v[200:203], v[106:109]
	v_mfma_i32_16x16x64_i8 v[92:95], v[48:51], v[208:211], v[92:95]
	v_mfma_i32_16x16x64_i8 v[88:91], v[64:67], v[208:211], v[88:91]
	v_mfma_i32_16x16x64_i8 v[142:145], v[52:55], v[176:179], v[142:145]
	v_mfma_i32_16x16x64_i8 v[138:141], v[68:71], v[176:179], v[138:141]
	v_mfma_i32_16x16x64_i8 v[126:129], v[52:55], v[190:193], v[126:129]
	v_mfma_i32_16x16x64_i8 v[122:125], v[68:71], v[190:193], v[122:125]
	v_mfma_i32_16x16x64_i8 v[110:113], v[52:55], v[204:207], v[110:113]
	v_mfma_i32_16x16x64_i8 v[106:109], v[68:71], v[204:207], v[106:109]
	v_mfma_i32_16x16x64_i8 v[92:95], v[52:55], v[212:215], v[92:95]
	v_mfma_i32_16x16x64_i8 v[88:91], v[68:71], v[212:215], v[88:91]
	s_setprio 0
	s_setprio 1
	v_mfma_i32_16x16x64_i8 v[134:137], v[156:159], v[172:175], v[134:137]
	v_mfma_i32_16x16x64_i8 v[130:133], v[164:167], v[172:175], v[130:133]
	v_mfma_i32_16x16x64_i8 v[118:121], v[156:159], v[180:183], v[118:121]
	v_mfma_i32_16x16x64_i8 v[114:117], v[164:167], v[180:183], v[114:117]
	v_mfma_i32_16x16x64_i8 v[102:105], v[156:159], v[200:203], v[102:105]
	v_mfma_i32_16x16x64_i8 v[98:101], v[164:167], v[200:203], v[98:101]
	v_mfma_i32_16x16x64_i8 v[84:87], v[156:159], v[208:211], v[84:87]
	v_mfma_i32_16x16x64_i8 v[80:83], v[164:167], v[208:211], v[80:83]
	v_mfma_i32_16x16x64_i8 v[134:137], v[160:163], v[176:179], v[134:137]
	v_mfma_i32_16x16x64_i8 v[130:133], v[168:171], v[176:179], v[130:133]
	v_mfma_i32_16x16x64_i8 v[118:121], v[160:163], v[190:193], v[118:121]
	v_mfma_i32_16x16x64_i8 v[114:117], v[168:171], v[190:193], v[114:117]
	v_mfma_i32_16x16x64_i8 v[102:105], v[160:163], v[204:207], v[102:105]
	v_mfma_i32_16x16x64_i8 v[98:101], v[168:171], v[204:207], v[98:101]
	v_mfma_i32_16x16x64_i8 v[84:87], v[160:163], v[212:215], v[84:87]
	v_mfma_i32_16x16x64_i8 v[80:83], v[168:171], v[212:215], v[80:83]
	s_setprio 0
	s_barrier
	s_add_i32 s70, s70, s75
	v_lshl_add_u64 v[184:185], s[54:55], 0, v[96:97]
	s_mov_b32 m0, s70
	ds_read_b128 v[172:175], v189 offset:16384
	ds_read_b128 v[176:179], v189 offset:17408
	ds_read_b128 v[180:183], v189 offset:18432
	ds_read_b128 v[190:193], v189 offset:19456
	ds_read_b128 v[200:203], v189 offset:20480
	ds_read_b128 v[204:207], v189 offset:21504
	ds_read_b128 v[208:211], v189 offset:22528
	ds_read_b128 v[212:215], v189 offset:23552
	global_load_lds_dwordx4 v[184:185], off
	s_add_i32 m0, s70, 0x2000
	s_add_u32 s76, s54, 0x80000
	v_lshl_add_u64 v[194:195], s[54:55], 0, v[150:151]
	s_addc_u32 s77, s55, 0
	s_add_i32 s70, s87, s75
	global_load_lds_dwordx4 v[194:195], off
	v_lshl_add_u64 v[216:217], s[76:77], 0, v[96:97]
	s_mov_b32 m0, s70
	v_lshl_add_u64 v[218:219], s[56:57], 0, v[148:149]
	global_load_lds_dwordx4 v[216:217], off
	v_lshl_add_u64 v[216:217], s[76:77], 0, v[150:151]
	s_add_i32 m0, s70, 0x2000
	s_nop 0
	global_load_lds_dwordx4 v[216:217], off
	v_lshl_add_u64 v[216:217], s[56:57], 0, v[146:147]
	s_mov_b32 m0, s80
	s_nop 0
	global_load_lds_dwordx4 v[216:217], off
	s_mov_b32 m0, s85
	s_nop 0
	global_load_lds_dwordx4 v[218:219], off
	s_cmp_eq_u32 s65, -2
	s_cbranch_scc1 .Ltb_g1b_2
	s_waitcnt vmcnt(8)
; #define PG8_STAGE(bufoff, gbase, voff) do { _Pragma("unroll") for (int _i = 0; _i < 2; ++_i) \
;         __builtin_amdgcn_global_load_lds((const unsigned*)((const char*)(gbase) + (voff)[_i]), (PG8_LAS unsigned*)(lds + (bufoff) + ldsw + _i * 8192), 16, 0, 0); } while (0)
; #define PG8_LDA(dst, b, h) do { _Pragma("unroll") for (int m = 0; m < 4; ++m) _Pragma("unroll") for (int k = 0; k < 2; ++k) dst[m][k] = *(const PG8_LAS bf16x8*)(lds + PG8_SA(b, h) + aoff + m * 2048 + k * 1024); } while (0)
; #define PG8_LDB(dst, b, h) do { _Pragma("unroll") for (int n = 0; n < 2; ++n) _Pragma("unroll") for (int k = 0; k < 2; ++k) dst[n][k] = *(const PG8_LAS bf16x8*)(lds + PG8_SB(b, h) + boff + n * 2048 + k * 1024); } while (0)
; #define PG8_MMA(ai, bj, At, Bt) do { __builtin_amdgcn_s_setprio(1); _Pragma("unroll") for (int m = 0; m < 4; ++m) _Pragma("unroll") for (int n = 0; n < 2; ++n) _Pragma("unroll") for (int k = 0; k < 2; ++k) \
;         mma1<I8>(acc[ai][bj][m][n], Bt[n][k], At[m][k]); __builtin_amdgcn_s_setprio(0); } while (0)
; #define PG8_WAIT_V(n) asm volatile("s_waitcnt vmcnt(" #n ")" ::: "memory")
; #define PG8_WAIT_L(n) asm volatile("s_waitcnt lgkmcnt(" #n ")" ::: "memory")
; #define PG8_BAR __builtin_amdgcn_s_barrier()
; #define PG8_SCHED __builtin_amdgcn_sched_barrier(0)
; template <class Epi, class Sched, bool ALIGN_EPI = false, bool SP2 = false, bool I8 = false>
; __device__ __forceinline__ void gemm_phase(PG8_LAS unsigned char* lds, const Gemm g, const Sched& S, const Epi& E, const int tid) {
;     ...
;             PG8_WAIT_V(8); PG8_WAIT_L(0); PG8_BAR; PG8_MMA(1, 0, At, B0); PG8_MMA(1, 1, At, B1); PG8_BAR; PG8_SCHED;
;             PG8_LDB(B0, 1, 0); PG8_LDB(B1, 1, 1); PG8_SCHED; PG8_LDA(At, 1, 0); PG8_STAGE(PG8_SA(0, 1), a2 + hstepA, voffA);
;             PG8_WAIT_V(8); PG8_WAIT_L(0); PG8_BAR; PG8_MMA(0, 0, At, B0); PG8_MMA(0, 1, At, B1); PG8_BAR; PG8_SCHED;
.Ltb_g1b_2:
	s_waitcnt lgkmcnt(0)
	s_barrier
	s_setprio 1
	s_waitcnt lgkmcnt(0)
	v_mfma_i32_16x16x64_i8 v[76:79], v[48:51], v[172:175], v[76:79]
	v_mfma_i32_16x16x64_i8 v[72:75], v[64:67], v[172:175], v[72:75]
	v_mfma_i32_16x16x64_i8 v[44:47], v[48:51], v[180:183], v[44:47]
	v_mfma_i32_16x16x64_i8 v[40:43], v[64:67], v[180:183], v[40:43]
	v_mfma_i32_16x16x64_i8 v[28:31], v[48:51], v[200:203], v[28:31]
	v_mfma_i32_16x16x64_i8 v[24:27], v[64:67], v[200:203], v[24:27]
	v_mfma_i32_16x16x64_i8 v[12:15], v[48:51], v[208:211], v[12:15]
	v_mfma_i32_16x16x64_i8 v[8:11], v[64:67], v[208:211], v[8:11]
	v_mfma_i32_16x16x64_i8 v[76:79], v[52:55], v[176:179], v[76:79]
	v_mfma_i32_16x16x64_i8 v[72:75], v[68:71], v[176:179], v[72:75]
	v_mfma_i32_16x16x64_i8 v[44:47], v[52:55], v[190:193], v[44:47]
	v_mfma_i32_16x16x64_i8 v[40:43], v[68:71], v[190:193], v[40:43]
	v_mfma_i32_16x16x64_i8 v[28:31], v[52:55], v[204:207], v[28:31]
	v_mfma_i32_16x16x64_i8 v[24:27], v[68:71], v[204:207], v[24:27]
	v_mfma_i32_16x16x64_i8 v[12:15], v[52:55], v[212:215], v[12:15]
	v_mfma_i32_16x16x64_i8 v[8:11], v[68:71], v[212:215], v[8:11]
	s_setprio 0
	s_setprio 1
	v_mfma_i32_16x16x64_i8 v[36:39], v[156:159], v[180:183], v[36:39]
	v_mfma_i32_16x16x64_i8 v[32:35], v[164:167], v[180:183], v[32:35]
	v_mfma_i32_16x16x64_i8 v[20:23], v[156:159], v[200:203], v[20:23]
	v_mfma_i32_16x16x64_i8 v[16:19], v[164:167], v[200:203], v[16:19]
	v_mfma_i32_16x16x64_i8 v[4:7], v[156:159], v[208:211], v[4:7]
	v_mfma_i32_16x16x64_i8 v[0:3], v[164:167], v[208:211], v[0:3]
	v_mfma_i32_16x16x64_i8 v[48:51], v[156:159], v[172:175], v[60:63]
	v_mfma_i32_16x16x64_i8 v[52:55], v[164:167], v[172:175], v[56:59]
	v_mfma_i32_16x16x64_i8 v[36:39], v[160:163], v[190:193], v[36:39]
	v_mfma_i32_16x16x64_i8 v[32:35], v[168:171], v[190:193], v[32:35]
	v_mfma_i32_16x16x64_i8 v[20:23], v[160:163], v[204:207], v[20:23]
	v_mfma_i32_16x16x64_i8 v[16:19], v[168:171], v[204:207], v[16:19]
	v_mfma_i32_16x16x64_i8 v[4:7], v[160:163], v[212:215], v[4:7]
	v_mfma_i32_16x16x64_i8 v[0:3], v[168:171], v[212:215], v[0:3]
	v_mfma_i32_16x16x64_i8 v[48:51], v[160:163], v[176:179], v[48:51]
	v_mfma_i32_16x16x64_i8 v[52:55], v[168:171], v[176:179], v[52:55]
	s_setprio 0
	s_barrier
	s_add_i32 s70, 0, 0x18000
	s_add_i32 s76, 0, 0x1c000
	v_add_u32_e32 v68, s70, v187
	v_add_u32_e32 v168, s76, v187
	ds_read_b128 v[56:59], v68
	ds_read_b128 v[60:63], v68 offset:1024
	ds_read_b128 v[64:67], v68 offset:2048
	ds_read_b128 v[68:71], v68 offset:3072
	ds_read_b128 v[156:159], v168
	ds_read_b128 v[160:163], v168 offset:1024
	ds_read_b128 v[164:167], v168 offset:2048
	ds_read_b128 v[168:171], v168 offset:3072
	s_add_u32 s56, s56, 0x80000
	s_addc_u32 s57, s57, 0
	s_mov_b32 m0, s86
	v_lshl_add_u64 v[220:221], s[56:57], 0, v[146:147]
	ds_read_b128 v[172:175], v189 offset:32768
	ds_read_b128 v[176:179], v189 offset:33792
	ds_read_b128 v[180:183], v189 offset:34816
	ds_read_b128 v[190:193], v189 offset:35840
	ds_read_b128 v[200:203], v189 offset:36864
	ds_read_b128 v[204:207], v189 offset:37888
	ds_read_b128 v[208:211], v189 offset:38912
	ds_read_b128 v[212:215], v189 offset:39936
	global_load_lds_dwordx4 v[220:221], off
	v_lshl_add_u64 v[220:221], s[56:57], 0, v[148:149]
	s_mov_b32 m0, s88
	s_nop 0
	global_load_lds_dwordx4 v[220:221], off
	s_waitcnt vmcnt(8)
	s_waitcnt lgkmcnt(0)
	s_barrier
	s_setprio 1
	s_waitcnt lgkmcnt(0)
	v_mfma_i32_16x16x64_i8 v[142:145], v[56:59], v[172:175], v[142:145]
	v_mfma_i32_16x16x64_i8 v[138:141], v[64:67], v[172:175], v[138:141]
	v_mfma_i32_16x16x64_i8 v[126:129], v[56:59], v[180:183], v[126:129]
	v_mfma_i32_16x16x64_i8 v[122:125], v[64:67], v[180:183], v[122:125]
	v_mfma_i32_16x16x64_i8 v[110:113], v[56:59], v[200:203], v[110:113]
	v_mfma_i32_16x16x64_i8 v[106:109], v[64:67], v[200:203], v[106:109]
	v_mfma_i32_16x16x64_i8 v[92:95], v[56:59], v[208:211], v[92:95]
	v_mfma_i32_16x16x64_i8 v[88:91], v[64:67], v[208:211], v[88:91]
	v_mfma_i32_16x16x64_i8 v[142:145], v[60:63], v[176:179], v[142:145]
	v_mfma_i32_16x16x64_i8 v[138:141], v[68:71], v[176:179], v[138:141]
	v_mfma_i32_16x16x64_i8 v[126:129], v[60:63], v[190:193], v[126:129]
	v_mfma_i32_16x16x64_i8 v[122:125], v[68:71], v[190:193], v[122:125]
	v_mfma_i32_16x16x64_i8 v[110:113], v[60:63], v[204:207], v[110:113]
	v_mfma_i32_16x16x64_i8 v[106:109], v[68:71], v[204:207], v[106:109]
	v_mfma_i32_16x16x64_i8 v[92:95], v[60:63], v[212:215], v[92:95]
	v_mfma_i32_16x16x64_i8 v[88:91], v[68:71], v[212:215], v[88:91]
	s_setprio 0
	s_setprio 1
	v_mfma_i32_16x16x64_i8 v[134:137], v[156:159], v[172:175], v[134:137]
	v_mfma_i32_16x16x64_i8 v[130:133], v[164:167], v[172:175], v[130:133]
	v_mfma_i32_16x16x64_i8 v[118:121], v[156:159], v[180:183], v[118:121]
	v_mfma_i32_16x16x64_i8 v[114:117], v[164:167], v[180:183], v[114:117]
	v_mfma_i32_16x16x64_i8 v[102:105], v[156:159], v[200:203], v[102:105]
	v_mfma_i32_16x16x64_i8 v[98:101], v[164:167], v[200:203], v[98:101]
	v_mfma_i32_16x16x64_i8 v[84:87], v[156:159], v[208:211], v[84:87]
	v_mfma_i32_16x16x64_i8 v[80:83], v[164:167], v[208:211], v[80:83]
	v_mfma_i32_16x16x64_i8 v[134:137], v[160:163], v[176:179], v[134:137]
	v_mfma_i32_16x16x64_i8 v[130:133], v[168:171], v[176:179], v[130:133]
	v_mfma_i32_16x16x64_i8 v[118:121], v[160:163], v[190:193], v[118:121]
	v_mfma_i32_16x16x64_i8 v[114:117], v[168:171], v[190:193], v[114:117]
	v_mfma_i32_16x16x64_i8 v[102:105], v[160:163], v[204:207], v[102:105]
	v_mfma_i32_16x16x64_i8 v[98:101], v[168:171], v[204:207], v[98:101]
	v_mfma_i32_16x16x64_i8 v[84:87], v[160:163], v[212:215], v[84:87]
	v_mfma_i32_16x16x64_i8 v[80:83], v[168:171], v[212:215], v[80:83]
	s_setprio 0
	s_barrier
; #define PG8_STAGE(bufoff, gbase, voff) do { _Pragma("unroll") for (int _i = 0; _i < 2; ++_i) \
;         __builtin_amdgcn_global_load_lds((const unsigned*)((const char*)(gbase) + (voff)[_i]), (PG8_LAS unsigned*)(lds + (bufoff) + ldsw + _i * 8192), 16, 0, 0); } while (0)
; #define PG8_LDA(dst, b, h) do { _Pragma("unroll") for (int m = 0; m < 4; ++m) _Pragma("unroll") for (int k = 0; k < 2; ++k) dst[m][k] = *(const PG8_LAS bf16x8*)(lds + PG8_SA(b, h) + aoff + m * 2048 + k * 1024); } while (0)
; #define PG8_MMA(ai, bj, At, Bt) do { __builtin_amdgcn_s_setprio(1); _Pragma("unroll") for (int m = 0; m < 4; ++m) _Pragma("unroll") for (int n = 0; n < 2; ++n) _Pragma("unroll") for (int k = 0; k < 2; ++k) \
;         mma1<I8>(acc[ai][bj][m][n], Bt[n][k], At[m][k]); __builtin_amdgcn_s_setprio(0); } while (0)
; #define PG8_WAIT_V(n) asm volatile("s_waitcnt vmcnt(" #n ")" ::: "memory")
; #define PG8_WAIT_L(n) asm volatile("s_waitcnt lgkmcnt(" #n ")" ::: "memory")
; #define PG8_BAR __builtin_amdgcn_s_barrier()
; #define PG8_SCHED __builtin_amdgcn_sched_barrier(0)
; template <class Epi, class Sched, bool ALIGN_EPI = false, bool SP2 = false, bool I8 = false>
; __device__ __forceinline__ void gemm_phase(PG8_LAS unsigned char* lds, const Gemm g, const Sched& S, const Epi& E, const int tid) {
;     ...
;             PG8_LDA(At, 1, 1); PG8_STAGE(PG8_SB(1, 0), b3, voffB); PG8_STAGE(PG8_SB(1, 1), b3 + hstepB, voffB); PG8_STAGE(PG8_SA(1, 0), a3, voffA);
;             PG8_WAIT_V(8); PG8_WAIT_L(0); PG8_BAR; PG8_MMA(1, 0, At, B0); PG8_MMA(1, 1, At, B1); PG8_BAR; PG8_SCHED;
	s_add_i32 s56, s70, s75
	v_lshl_add_u64 v[184:185], v[184:185], 0, s[42:43]
	s_mov_b32 m0, s56
	ds_read_b128 v[172:175], v189 offset:49152
	ds_read_b128 v[176:179], v189 offset:50176
	ds_read_b128 v[180:183], v189 offset:51200
	ds_read_b128 v[190:193], v189 offset:52224
	ds_read_b128 v[200:203], v189 offset:53248
	ds_read_b128 v[204:207], v189 offset:54272
	ds_read_b128 v[208:211], v189 offset:55296
	ds_read_b128 v[212:215], v189 offset:56320
	global_load_lds_dwordx4 v[184:185], off
	s_add_i32 m0, s56, 0x2000
	s_add_u32 s54, s54, 0x80080
	v_lshl_add_u64 v[184:185], v[194:195], 0, s[42:43]
	s_addc_u32 s55, s55, 0
	s_add_i32 s56, s76, s75
	global_load_lds_dwordx4 v[184:185], off
	v_lshl_add_u64 v[184:185], s[54:55], 0, v[96:97]
	s_mov_b32 m0, s56
	s_nop 0
	global_load_lds_dwordx4 v[184:185], off
	v_lshl_add_u64 v[184:185], s[54:55], 0, v[150:151]
	s_add_i32 m0, s56, 0x2000
	s_nop 0
	global_load_lds_dwordx4 v[184:185], off
	v_lshl_add_u64 v[184:185], v[216:217], 0, s[42:43]
	s_mov_b32 m0, s89
	s_nop 0
	global_load_lds_dwordx4 v[184:185], off
	v_lshl_add_u64 v[184:185], v[218:219], 0, s[42:43]
	s_mov_b32 m0, s90
	s_nop 0
	global_load_lds_dwordx4 v[184:185], off
	s_waitcnt vmcnt(8)
	s_waitcnt lgkmcnt(0)
	s_barrier
	s_setprio 1
	s_waitcnt lgkmcnt(0)
	v_mfma_i32_16x16x64_i8 v[76:79], v[56:59], v[172:175], v[76:79]
	v_mfma_i32_16x16x64_i8 v[72:75], v[64:67], v[172:175], v[72:75]
	v_mfma_i32_16x16x64_i8 v[44:47], v[56:59], v[180:183], v[44:47]
	v_mfma_i32_16x16x64_i8 v[40:43], v[64:67], v[180:183], v[40:43]
	v_mfma_i32_16x16x64_i8 v[28:31], v[56:59], v[200:203], v[28:31]
	v_mfma_i32_16x16x64_i8 v[24:27], v[64:67], v[200:203], v[24:27]
	v_mfma_i32_16x16x64_i8 v[12:15], v[56:59], v[208:211], v[12:15]
	v_mfma_i32_16x16x64_i8 v[8:11], v[64:67], v[208:211], v[8:11]
	v_mfma_i32_16x16x64_i8 v[76:79], v[60:63], v[176:179], v[76:79]
	v_mfma_i32_16x16x64_i8 v[72:75], v[68:71], v[176:179], v[72:75]
	v_mfma_i32_16x16x64_i8 v[44:47], v[60:63], v[190:193], v[44:47]
	v_mfma_i32_16x16x64_i8 v[40:43], v[68:71], v[190:193], v[40:43]
	v_mfma_i32_16x16x64_i8 v[28:31], v[60:63], v[204:207], v[28:31]
	v_mfma_i32_16x16x64_i8 v[24:27], v[68:71], v[204:207], v[24:27]
	v_mfma_i32_16x16x64_i8 v[12:15], v[60:63], v[212:215], v[12:15]
	v_mfma_i32_16x16x64_i8 v[8:11], v[68:71], v[212:215], v[8:11]
	s_setprio 0
	s_setprio 1
	v_mfma_i32_16x16x64_i8 v[48:51], v[156:159], v[172:175], v[48:51]
	v_mfma_i32_16x16x64_i8 v[60:63], v[160:163], v[176:179], v[48:51]
	v_mfma_i32_16x16x64_i8 v[48:51], v[164:167], v[172:175], v[52:55]
	v_mfma_i32_16x16x64_i8 v[36:39], v[156:159], v[180:183], v[36:39]
	v_mfma_i32_16x16x64_i8 v[32:35], v[164:167], v[180:183], v[32:35]
	v_mfma_i32_16x16x64_i8 v[20:23], v[156:159], v[200:203], v[20:23]
	v_mfma_i32_16x16x64_i8 v[16:19], v[164:167], v[200:203], v[16:19]
	v_mfma_i32_16x16x64_i8 v[4:7], v[156:159], v[208:211], v[4:7]
	v_mfma_i32_16x16x64_i8 v[0:3], v[164:167], v[208:211], v[0:3]
	v_mfma_i32_16x16x64_i8 v[56:59], v[168:171], v[176:179], v[48:51]
	v_mfma_i32_16x16x64_i8 v[36:39], v[160:163], v[190:193], v[36:39]
	v_mfma_i32_16x16x64_i8 v[32:35], v[168:171], v[190:193], v[32:35]
	v_mfma_i32_16x16x64_i8 v[20:23], v[160:163], v[204:207], v[20:23]
	v_mfma_i32_16x16x64_i8 v[16:19], v[168:171], v[204:207], v[16:19]
	v_mfma_i32_16x16x64_i8 v[4:7], v[160:163], v[212:215], v[4:7]
	v_mfma_i32_16x16x64_i8 v[0:3], v[168:171], v[212:215], v[0:3]
	s_setprio 0
	s_barrier
	s_add_i32 s65, s65, 2
	s_add_u32 s49, s49, 0x100
	s_addc_u32 s60, s60, 0
	s_add_u32 s46, s46, 0x100
	s_addc_u32 s47, s47, 0
	s_cmp_gt_u32 s65, 29
	s_cbranch_scc0 .LBB0_335
	s_and_b64 vcc, exec, s[26:27]
	s_cbranch_vccz .LBB0_338
	s_barrier

; __device__ __forceinline__ unsigned cvt_pk_bf16(float lo, float hi) { const f32x2_t_ v = {lo, hi}; return __builtin_bit_cast(unsigned, __builtin_convertvector(v, bf16x2_t_)); }
; __device__ __forceinline__ float sigmoidf_(float x) { return __builtin_amdgcn_rcpf(1.0f + __expf(-x)); }
;     __device__ __forceinline__ void operator()(const f32x4 (&acc)[2][2][4][2], const Unit& u, int wr, int wc, int fr, int fq) const {
;     ...
;                 for (int bj = 0; bj < 2; ++bj) { f32x4 v0 = acc[ai][bj][m][0], v1 = acc[ai][bj][m][1];
;                     if (u.pn >= sig_from) {
; #pragma unroll
;                         for (int e = 0; e < 4; ++e) { v0[e] = sigmoidf_(v0[e]); v1[e] = sigmoidf_(v1[e]); } }
;                     u32x4 w; w.x = cvt_pk_bf16(v0[0], v0[1]); w.y = cvt_pk_bf16(v0[2], v0[3]); w.z = cvt_pk_bf16(v1[0], v1[1]); w.w = cvt_pk_bf16(v1[2], v1[3]);
;                     *(u32x4*)(rowp + bj * HALF) = w; } }
; template <class Epi, class Sched, bool ALIGN_EPI = false, bool SP2 = false, bool I8 = false>
; __device__ __forceinline__ void gemm_phase(PG8_LAS unsigned char* lds, const Gemm g, const Sched& S, const Epi& E, const int tid) {
;     ...
;         if constexpr (!Epi::AFTER_DRAIN) { E(acc, cur, wr, wc, fr, fq); S.done(cur); }
;         if (!has_next) break;
.LBB0_402:
	v_cvt_pk_bf16_f32 v0, v0, v1
	v_cvt_pk_bf16_f32 v1, v4, v5
	v_cvt_pk_bf16_f32 v2, v2, v3
	v_cvt_pk_bf16_f32 v3, v6, v7
	s_andn2_b64 vcc, exec, s[36:37]
	s_mov_b64 s[4:5], -1
	global_store_dwordx4 v[8:9], v[0:3], off offset:256
	s_waitcnt vmcnt(16)
	s_cbranch_vccnz .LBB0_304
	s_andn2_b64 vcc, exec, s[10:11]
	s_cbranch_vccnz .LBB0_303
	s_barrier
	s_branch .LBB0_303
